# v21 + K-loop heads of P1/P3/P4/P5 aligned to 64 bytes
# baseline (speedup 1.0000x reference)
; #define PG8_STAGE(bufoff, gbase, voff) do { _Pragma("unroll") for (int _i = 0; _i < 2; ++_i) \
;         __builtin_amdgcn_global_load_lds((const unsigned*)((const char*)(gbase) + (voff)[_i]), (PG8_LAS unsigned*)(lds + (bufoff) + ldsw + _i * 8192), 16, 0, 0); } while (0)
; #define PG8_LDA(dst, b, h) do { _Pragma("unroll") for (int m = 0; m < 4; ++m) _Pragma("unroll") for (int k = 0; k < 2; ++k) dst[m][k] = *(const PG8_LAS bf16x8*)(lds + PG8_SA(b, h) + aoff + m * 2048 + k * 1024); } while (0)
; #define PG8_LDB(dst, b, h) do { _Pragma("unroll") for (int n = 0; n < 2; ++n) _Pragma("unroll") for (int k = 0; k < 2; ++k) dst[n][k] = *(const PG8_LAS bf16x8*)(lds + PG8_SB(b, h) + boff + n * 2048 + k * 1024); } while (0)
; #define PG8_WAIT_V(n) asm volatile("s_waitcnt vmcnt(" #n ")" ::: "memory")
; #define PG8_WAIT_L(n) asm volatile("s_waitcnt lgkmcnt(" #n ")" ::: "memory")
; #define PG8_BAR __builtin_amdgcn_s_barrier()
; template <class Epi, class Sched, bool ALIGN_EPI = false, bool SP2 = false, bool ABLK = false>
; __device__ __forceinline__ void gemm_phase(PG8_LAS unsigned char* lds, const Gemm g, const Sched& S, const Epi& E) {
;     ...
;         const char* nA = has_next ? (const char*)g.A + (size_t)nxt.pm * tstepA : cA; const char* nB = has_next ? (const char*)g.Bt + (size_t)nxt.pn * tstep : cB;
;         for (int t = 0; t < nt; t += 2) {
;             if constexpr (Epi::MID) { if (t == nt / 2) E.mid(acc, cur, wr, wc, fr, fq); }
;             const bool last = (t == nt - 2);
;             const char* a1 = cA + (size_t)(t + 1) * kstepA;
;             const char* a2 = last ? nA : cA + (size_t)(t + 2) * kstepA; const char* b2 = last ? nB : cB + (size_t)(t + 2) * kstep;
;             const char* a3 = a2 + kstepA; const char* b3 = b2 + kstep;
;             if (last && has_next) S.a_ready(nxt);
;             if constexpr (SP2) {
;             PG8_LDB(B0, 0, 0); PG8_LDB(B1, 0, 1); PG8_SCHED; PG8_LDA(At, 0, 0); PG8_STAGE(PG8_SA(1, 1), a1 + hstepA, voffA);
;             PG8_WAIT_V(8); PG8_WAIT_L(0); PG8_BAR; PG8_MMA(0, 0, At, B0); PG8_MMA(0, 1, At, B1); PG8_BAR; PG8_SCHED;
;             PG8_LDA(At, 0, 1); PG8_STAGE(PG8_SB(0, 0), b2, voffB); PG8_STAGE(PG8_SB(0, 1), b2 + hstep, voffB); PG8_STAGE(PG8_SA(0, 0), a2, voffA);
;             PG8_WAIT_V(8); PG8_WAIT_L(0); PG8_BAR; PG8_MMA(1, 0, At, B0); PG8_MMA(1, 1, At, B1); PG8_BAR; PG8_SCHED;
.LBB0_214:
	s_ashr_i32 s5, s4, 31
	s_lshl_b64 s[6:7], s[4:5], 19
	s_add_u32 s8, s62, s6
	s_addc_u32 s9, s63, s7
	s_and_b64 s[6:7], s[36:37], exec
	s_cselect_b32 s5, s9, s99
	s_cselect_b32 s21, s8, s98
	s_ashr_i32 s95, s94, 31
	s_lshl_b64 s[6:7], s[94:95], 19
	s_add_u32 s6, s74, s6
	s_addc_u32 s7, s75, s7
	s_and_b64 s[22:23], s[36:37], exec
	s_cselect_b32 s95, s7, s1
	s_cselect_b32 s22, s6, s0
	s_add_u32 vcc_lo, s98, 0x40080
	s_addc_u32 vcc_hi, s99, 0
	s_add_u32 s23, s0, 0x100
	s_addc_u32 s24, s1, 0
	s_mov_b32 s25, -2
	ds_read_b128 v[166:169], v163
	ds_read_b128 v[170:173], v163 offset:1024
	ds_read_b128 v[180:183], v163 offset:2048
	ds_read_b128 v[184:187], v163 offset:3072
	ds_read_b128 v[188:191], v164
	ds_read_b128 v[192:195], v164 offset:1024
	ds_read_b128 v[196:199], v164 offset:2048
	ds_read_b128 v[200:203], v164 offset:3072
	s_add_u32 s0, vcc_lo, 0xfffc0080
	s_addc_u32 s1, vcc_hi, -1
	s_cmp_eq_u32 s25, 12
	s_cselect_b32 s99, s5, s1
	s_cselect_b32 s98, s21, s0
	s_cselect_b32 s1, s95, s24
	s_cselect_b32 s0, s22, s23
	v_lshl_add_u64 v[176:177], vcc, 0, v[142:143]
	s_add_i32 m0, s97, 0xc000
	ds_read_b128 v[204:207], v165
	ds_read_b128 v[208:211], v165 offset:1024
	ds_read_b128 v[212:215], v165 offset:2048
	ds_read_b128 v[216:219], v165 offset:3072
	ds_read_b128 v[220:223], v165 offset:4096
	ds_read_b128 v[224:227], v165 offset:5120
	ds_read_b128 v[228:231], v165 offset:6144
	ds_read_b128 v[232:235], v165 offset:7168
	global_load_lds_dwordx4 v[176:177], off
	v_lshl_add_u64 v[176:177], vcc, 0, v[144:145]
	s_add_i32 m0, s97, 0xe000
	s_nop 0
	global_load_lds_dwordx4 v[176:177], off
	s_waitcnt vmcnt(8)
	s_waitcnt lgkmcnt(0)
	s_barrier
	s_setprio 1
	s_waitcnt lgkmcnt(0)
	v_mfma_f32_16x16x32_bf16 v[124:127], v[166:169], v[204:207], 0
	v_mfma_f32_16x16x32_bf16 v[120:123], v[180:183], v[204:207], 0
	v_mfma_f32_16x16x32_bf16 v[116:119], v[166:169], v[212:215], 0
	v_mfma_f32_16x16x32_bf16 v[108:111], v[180:183], v[212:215], 0
	v_mfma_f32_16x16x32_bf16 v[100:103], v[166:169], v[220:223], 0
	v_mfma_f32_16x16x32_bf16 v[92:95], v[180:183], v[220:223], 0
	v_mfma_f32_16x16x32_bf16 v[84:87], v[166:169], v[228:231], 0
	v_mfma_f32_16x16x32_bf16 v[76:79], v[180:183], v[228:231], 0
	v_mfma_f32_16x16x32_bf16 v[124:127], v[170:173], v[208:211], v[124:127]
	v_mfma_f32_16x16x32_bf16 v[120:123], v[184:187], v[208:211], v[120:123]
	v_mfma_f32_16x16x32_bf16 v[116:119], v[170:173], v[216:219], v[116:119]
	v_mfma_f32_16x16x32_bf16 v[108:111], v[184:187], v[216:219], v[108:111]
	v_mfma_f32_16x16x32_bf16 v[100:103], v[170:173], v[224:227], v[100:103]
	v_mfma_f32_16x16x32_bf16 v[92:95], v[184:187], v[224:227], v[92:95]
	v_mfma_f32_16x16x32_bf16 v[84:87], v[170:173], v[232:235], v[84:87]
	v_mfma_f32_16x16x32_bf16 v[76:79], v[184:187], v[232:235], v[76:79]
	s_setprio 0
	s_setprio 1
	v_mfma_f32_16x16x32_bf16 v[112:115], v[188:191], v[204:207], 0
	v_mfma_f32_16x16x32_bf16 v[104:107], v[196:199], v[204:207], 0
	v_mfma_f32_16x16x32_bf16 v[96:99], v[188:191], v[212:215], 0
	v_mfma_f32_16x16x32_bf16 v[88:91], v[196:199], v[212:215], 0
	v_mfma_f32_16x16x32_bf16 v[80:83], v[188:191], v[220:223], 0
	v_mfma_f32_16x16x32_bf16 v[72:75], v[196:199], v[220:223], 0
	v_mfma_f32_16x16x32_bf16 v[68:71], v[188:191], v[228:231], 0
	v_mfma_f32_16x16x32_bf16 v[64:67], v[196:199], v[228:231], 0
	v_mfma_f32_16x16x32_bf16 v[112:115], v[192:195], v[208:211], v[112:115]
	v_mfma_f32_16x16x32_bf16 v[104:107], v[200:203], v[208:211], v[104:107]
	v_mfma_f32_16x16x32_bf16 v[96:99], v[192:195], v[216:219], v[96:99]
	v_mfma_f32_16x16x32_bf16 v[88:91], v[200:203], v[216:219], v[88:91]
	v_mfma_f32_16x16x32_bf16 v[80:83], v[192:195], v[224:227], v[80:83]
	v_mfma_f32_16x16x32_bf16 v[72:75], v[200:203], v[224:227], v[72:75]
	v_mfma_f32_16x16x32_bf16 v[68:71], v[192:195], v[232:235], v[68:71]
	v_mfma_f32_16x16x32_bf16 v[64:67], v[200:203], v[232:235], v[64:67]
	s_setprio 0
	s_barrier
	s_add_i32 s26, s17, s46
	v_lshl_add_u64 v[176:177], s[0:1], 0, v[136:137]
	s_mov_b32 m0, s26
	ds_read_b128 v[204:207], v165 offset:16384
	ds_read_b128 v[208:211], v165 offset:17408
	ds_read_b128 v[212:215], v165 offset:18432
	ds_read_b128 v[216:219], v165 offset:19456
	ds_read_b128 v[220:223], v165 offset:20480
	ds_read_b128 v[224:227], v165 offset:21504
	ds_read_b128 v[228:231], v165 offset:22528
	ds_read_b128 v[232:235], v165 offset:23552
	global_load_lds_dwordx4 v[176:177], off
	s_add_i32 m0, s26, 0x2000
	s_add_u32 s26, s0, 0x40000
	v_lshl_add_u64 v[236:237], s[0:1], 0, v[132:133]
	s_addc_u32 s27, s1, 0
	s_add_i32 s28, s18, s46
	global_load_lds_dwordx4 v[236:237], off
	v_lshl_add_u64 v[238:239], s[26:27], 0, v[136:137]
	s_mov_b32 m0, s28
	v_lshl_add_u64 v[240:241], s[98:99], 0, v[134:135]
	global_load_lds_dwordx4 v[238:239], off
	v_lshl_add_u64 v[238:239], s[26:27], 0, v[132:133]
	s_add_i32 m0, s28, 0x2000
	s_nop 0
	global_load_lds_dwordx4 v[238:239], off
	v_lshl_add_u64 v[238:239], s[98:99], 0, v[138:139]
	s_mov_b32 m0, s97
	s_nop 0
	global_load_lds_dwordx4 v[238:239], off
	s_mov_b32 m0, s10
	s_nop 0
	global_load_lds_dwordx4 v[240:241], off
	s_waitcnt vmcnt(8)
	s_waitcnt lgkmcnt(0)
	s_barrier
; #define PG8_STAGE(bufoff, gbase, voff) do { _Pragma("unroll") for (int _i = 0; _i < 2; ++_i) \
;         __builtin_amdgcn_global_load_lds((const unsigned*)((const char*)(gbase) + (voff)[_i]), (PG8_LAS unsigned*)(lds + (bufoff) + ldsw + _i * 8192), 16, 0, 0); } while (0)
; #define PG8_LDA(dst, b, h) do { _Pragma("unroll") for (int m = 0; m < 4; ++m) _Pragma("unroll") for (int k = 0; k < 2; ++k) dst[m][k] = *(const PG8_LAS bf16x8*)(lds + PG8_SA(b, h) + aoff + m * 2048 + k * 1024); } while (0)
; #define PG8_LDB(dst, b, h) do { _Pragma("unroll") for (int n = 0; n < 2; ++n) _Pragma("unroll") for (int k = 0; k < 2; ++k) dst[n][k] = *(const PG8_LAS bf16x8*)(lds + PG8_SB(b, h) + boff + n * 2048 + k * 1024); } while (0)
; #define PG8_MMA(ai, bj, At, Bt) do { __builtin_amdgcn_s_setprio(1); _Pragma("unroll") for (int m = 0; m < 4; ++m) _Pragma("unroll") for (int n = 0; n < 2; ++n) _Pragma("unroll") for (int k = 0; k < 2; ++k) \
;         acc[ai][bj][m][n] = __builtin_amdgcn_mfma_f32_16x16x32_bf16(Bt[n][k], At[m][k], acc[ai][bj][m][n], 0, 0, 0); __builtin_amdgcn_s_setprio(0); } while (0)
; #define PG8_WAIT_V(n) asm volatile("s_waitcnt vmcnt(" #n ")" ::: "memory")
; #define PG8_WAIT_L(n) asm volatile("s_waitcnt lgkmcnt(" #n ")" ::: "memory")
; #define PG8_BAR __builtin_amdgcn_s_barrier()
; #define PG8_SCHED __builtin_amdgcn_sched_barrier(0)
; template <class Epi, class Sched, bool ALIGN_EPI = false, bool SP2 = false, bool ABLK = false>
; __device__ __forceinline__ void gemm_phase(PG8_LAS unsigned char* lds, const Gemm g, const Sched& S, const Epi& E) {
;     ...
;             PG8_WAIT_V(8); PG8_WAIT_L(0); PG8_BAR; PG8_MMA(1, 0, At, B0); PG8_MMA(1, 1, At, B1); PG8_BAR; PG8_SCHED;
;             PG8_LDB(B0, 1, 0); PG8_LDB(B1, 1, 1); PG8_SCHED; PG8_LDA(At, 1, 0); PG8_STAGE(PG8_SA(0, 1), a2 + hstepA, voffA);
;             PG8_WAIT_V(8); PG8_WAIT_L(0); PG8_BAR; PG8_MMA(0, 0, At, B0); PG8_MMA(0, 1, At, B1); PG8_BAR; PG8_SCHED;
	s_setprio 1
	s_waitcnt lgkmcnt(0)
	v_mfma_f32_16x16x32_bf16 v[60:63], v[166:169], v[204:207], 0
	v_mfma_f32_16x16x32_bf16 v[56:59], v[180:183], v[204:207], 0
	v_mfma_f32_16x16x32_bf16 v[52:55], v[166:169], v[212:215], 0
	v_mfma_f32_16x16x32_bf16 v[44:47], v[180:183], v[212:215], 0
	v_mfma_f32_16x16x32_bf16 v[36:39], v[166:169], v[220:223], 0
	v_mfma_f32_16x16x32_bf16 v[28:31], v[180:183], v[220:223], 0
	v_mfma_f32_16x16x32_bf16 v[20:23], v[166:169], v[228:231], 0
	v_mfma_f32_16x16x32_bf16 v[12:15], v[180:183], v[228:231], 0
	v_mfma_f32_16x16x32_bf16 v[60:63], v[170:173], v[208:211], v[60:63]
	v_mfma_f32_16x16x32_bf16 v[56:59], v[184:187], v[208:211], v[56:59]
	v_mfma_f32_16x16x32_bf16 v[52:55], v[170:173], v[216:219], v[52:55]
	v_mfma_f32_16x16x32_bf16 v[44:47], v[184:187], v[216:219], v[44:47]
	v_mfma_f32_16x16x32_bf16 v[36:39], v[170:173], v[224:227], v[36:39]
	v_mfma_f32_16x16x32_bf16 v[28:31], v[184:187], v[224:227], v[28:31]
	v_mfma_f32_16x16x32_bf16 v[20:23], v[170:173], v[232:235], v[20:23]
	v_mfma_f32_16x16x32_bf16 v[12:15], v[184:187], v[232:235], v[12:15]
	s_setprio 0
	s_setprio 1
	v_mfma_f32_16x16x32_bf16 v[48:51], v[188:191], v[204:207], 0
	v_mfma_f32_16x16x32_bf16 v[40:43], v[196:199], v[204:207], 0
	v_mfma_f32_16x16x32_bf16 v[32:35], v[188:191], v[212:215], 0
	v_mfma_f32_16x16x32_bf16 v[24:27], v[196:199], v[212:215], 0
	v_mfma_f32_16x16x32_bf16 v[16:19], v[188:191], v[220:223], 0
	v_mfma_f32_16x16x32_bf16 v[8:11], v[196:199], v[220:223], 0
	v_mfma_f32_16x16x32_bf16 v[4:7], v[188:191], v[228:231], 0
	v_mfma_f32_16x16x32_bf16 v[0:3], v[196:199], v[228:231], 0
	v_mfma_f32_16x16x32_bf16 v[48:51], v[192:195], v[208:211], v[48:51]
	v_mfma_f32_16x16x32_bf16 v[40:43], v[200:203], v[208:211], v[40:43]
	v_mfma_f32_16x16x32_bf16 v[32:35], v[192:195], v[216:219], v[32:35]
	v_mfma_f32_16x16x32_bf16 v[24:27], v[200:203], v[216:219], v[24:27]
	v_mfma_f32_16x16x32_bf16 v[16:19], v[192:195], v[224:227], v[16:19]
	v_mfma_f32_16x16x32_bf16 v[8:11], v[200:203], v[224:227], v[8:11]
	v_mfma_f32_16x16x32_bf16 v[4:7], v[192:195], v[232:235], v[4:7]
	v_mfma_f32_16x16x32_bf16 v[0:3], v[200:203], v[232:235], v[0:3]
	s_setprio 0
	s_barrier
	s_add_i32 s28, 0, 0x18000
	v_add_u32_e32 v140, s28, v161
	s_add_i32 s29, 0, 0x1c000
	ds_read_b128 v[166:169], v140
	ds_read_b128 v[170:173], v140 offset:1024
	ds_read_b128 v[180:183], v140 offset:2048
	ds_read_b128 v[184:187], v140 offset:3072
	v_add_u32_e32 v140, s29, v161
	ds_read_b128 v[188:191], v140
	ds_read_b128 v[192:195], v140 offset:1024
	ds_read_b128 v[196:199], v140 offset:2048
	ds_read_b128 v[200:203], v140 offset:3072
	s_add_u32 s26, s98, 0x40000
	s_addc_u32 s27, s99, 0
	s_mov_b32 m0, s11
	v_lshl_add_u64 v[242:243], s[26:27], 0, v[138:139]
	ds_read_b128 v[204:207], v165 offset:32768
	ds_read_b128 v[208:211], v165 offset:33792
	ds_read_b128 v[212:215], v165 offset:34816
	ds_read_b128 v[216:219], v165 offset:35840
	ds_read_b128 v[220:223], v165 offset:36864
	ds_read_b128 v[224:227], v165 offset:37888
	ds_read_b128 v[228:231], v165 offset:38912
	ds_read_b128 v[232:235], v165 offset:39936
	global_load_lds_dwordx4 v[242:243], off
	v_lshl_add_u64 v[242:243], s[26:27], 0, v[134:135]
	s_mov_b32 m0, s12
	s_nop 0
	global_load_lds_dwordx4 v[242:243], off
	s_waitcnt vmcnt(8)
	s_waitcnt lgkmcnt(0)
	s_barrier
	s_setprio 1
	s_waitcnt lgkmcnt(0)
	v_mfma_f32_16x16x32_bf16 v[124:127], v[166:169], v[204:207], v[124:127]
	v_mfma_f32_16x16x32_bf16 v[120:123], v[180:183], v[204:207], v[120:123]
	v_mfma_f32_16x16x32_bf16 v[116:119], v[166:169], v[212:215], v[116:119]
	v_mfma_f32_16x16x32_bf16 v[108:111], v[180:183], v[212:215], v[108:111]
	v_mfma_f32_16x16x32_bf16 v[100:103], v[166:169], v[220:223], v[100:103]
	v_mfma_f32_16x16x32_bf16 v[92:95], v[180:183], v[220:223], v[92:95]
	v_mfma_f32_16x16x32_bf16 v[84:87], v[166:169], v[228:231], v[84:87]
	v_mfma_f32_16x16x32_bf16 v[76:79], v[180:183], v[228:231], v[76:79]
	v_mfma_f32_16x16x32_bf16 v[124:127], v[170:173], v[208:211], v[124:127]
	v_mfma_f32_16x16x32_bf16 v[120:123], v[184:187], v[208:211], v[120:123]
	v_mfma_f32_16x16x32_bf16 v[116:119], v[170:173], v[216:219], v[116:119]
	v_mfma_f32_16x16x32_bf16 v[108:111], v[184:187], v[216:219], v[108:111]
	v_mfma_f32_16x16x32_bf16 v[100:103], v[170:173], v[224:227], v[100:103]
	v_mfma_f32_16x16x32_bf16 v[92:95], v[184:187], v[224:227], v[92:95]
	v_mfma_f32_16x16x32_bf16 v[84:87], v[170:173], v[232:235], v[84:87]
	v_mfma_f32_16x16x32_bf16 v[76:79], v[184:187], v[232:235], v[76:79]
	s_setprio 0
	s_setprio 1
	v_mfma_f32_16x16x32_bf16 v[112:115], v[188:191], v[204:207], v[112:115]
	v_mfma_f32_16x16x32_bf16 v[104:107], v[196:199], v[204:207], v[104:107]
	v_mfma_f32_16x16x32_bf16 v[96:99], v[188:191], v[212:215], v[96:99]
	v_mfma_f32_16x16x32_bf16 v[88:91], v[196:199], v[212:215], v[88:91]
	v_mfma_f32_16x16x32_bf16 v[80:83], v[188:191], v[220:223], v[80:83]
	v_mfma_f32_16x16x32_bf16 v[72:75], v[196:199], v[220:223], v[72:75]
	v_mfma_f32_16x16x32_bf16 v[68:71], v[188:191], v[228:231], v[68:71]
	v_mfma_f32_16x16x32_bf16 v[64:67], v[196:199], v[228:231], v[64:67]
	v_mfma_f32_16x16x32_bf16 v[112:115], v[192:195], v[208:211], v[112:115]
	v_mfma_f32_16x16x32_bf16 v[104:107], v[200:203], v[208:211], v[104:107]
	v_mfma_f32_16x16x32_bf16 v[96:99], v[192:195], v[216:219], v[96:99]
	v_mfma_f32_16x16x32_bf16 v[88:91], v[200:203], v[216:219], v[88:91]
	v_mfma_f32_16x16x32_bf16 v[80:83], v[192:195], v[224:227], v[80:83]
	v_mfma_f32_16x16x32_bf16 v[72:75], v[200:203], v[224:227], v[72:75]
	v_mfma_f32_16x16x32_bf16 v[68:71], v[192:195], v[232:235], v[68:71]
	v_mfma_f32_16x16x32_bf16 v[64:67], v[200:203], v[232:235], v[64:67]
	s_setprio 0
	s_barrier
; #define PG8_STAGE(bufoff, gbase, voff) do { _Pragma("unroll") for (int _i = 0; _i < 2; ++_i) \
;         __builtin_amdgcn_global_load_lds((const unsigned*)((const char*)(gbase) + (voff)[_i]), (PG8_LAS unsigned*)(lds + (bufoff) + ldsw + _i * 8192), 16, 0, 0); } while (0)
; #define PG8_LDA(dst, b, h) do { _Pragma("unroll") for (int m = 0; m < 4; ++m) _Pragma("unroll") for (int k = 0; k < 2; ++k) dst[m][k] = *(const PG8_LAS bf16x8*)(lds + PG8_SA(b, h) + aoff + m * 2048 + k * 1024); } while (0)
; #define PG8_MMA(ai, bj, At, Bt) do { __builtin_amdgcn_s_setprio(1); _Pragma("unroll") for (int m = 0; m < 4; ++m) _Pragma("unroll") for (int n = 0; n < 2; ++n) _Pragma("unroll") for (int k = 0; k < 2; ++k) \
;         acc[ai][bj][m][n] = __builtin_amdgcn_mfma_f32_16x16x32_bf16(Bt[n][k], At[m][k], acc[ai][bj][m][n], 0, 0, 0); __builtin_amdgcn_s_setprio(0); } while (0)
; #define PG8_WAIT_V(n) asm volatile("s_waitcnt vmcnt(" #n ")" ::: "memory")
; #define PG8_WAIT_L(n) asm volatile("s_waitcnt lgkmcnt(" #n ")" ::: "memory")
; #define PG8_BAR __builtin_amdgcn_s_barrier()
; #define PG8_SCHED __builtin_amdgcn_sched_barrier(0)
; template <class Epi, class Sched, bool ALIGN_EPI = false, bool SP2 = false, bool ABLK = false>
; __device__ __forceinline__ void gemm_phase(PG8_LAS unsigned char* lds, const Gemm g, const Sched& S, const Epi& E) {
;     ...
;         for (int t = 0; t < nt; t += 2) {
;     ...
;             PG8_LDA(At, 1, 1); PG8_STAGE(PG8_SB(1, 0), b3, voffB); PG8_STAGE(PG8_SB(1, 1), b3 + hstep, voffB); PG8_STAGE(PG8_SA(1, 0), a3, voffA);
;             PG8_WAIT_V(8); PG8_WAIT_L(0); PG8_BAR; PG8_MMA(1, 0, At, B0); PG8_MMA(1, 1, At, B1); PG8_BAR; PG8_SCHED;
	s_add_i32 s26, s28, s46
	v_lshl_add_u64 v[176:177], v[176:177], 0, s[52:53]
	s_mov_b32 m0, s26
	ds_read_b128 v[204:207], v165 offset:49152
	ds_read_b128 v[208:211], v165 offset:50176
	ds_read_b128 v[212:215], v165 offset:51200
	ds_read_b128 v[216:219], v165 offset:52224
	ds_read_b128 v[220:223], v165 offset:53248
	ds_read_b128 v[224:227], v165 offset:54272
	ds_read_b128 v[228:231], v165 offset:55296
	ds_read_b128 v[232:235], v165 offset:56320
	global_load_lds_dwordx4 v[176:177], off
	s_add_i32 m0, s26, 0x2000
	s_add_u32 s0, s0, 0x40080
	v_lshl_add_u64 v[176:177], v[236:237], 0, s[52:53]
	s_addc_u32 s1, s1, 0
	s_add_i32 s26, s29, s46
	global_load_lds_dwordx4 v[176:177], off
	v_lshl_add_u64 v[176:177], s[0:1], 0, v[136:137]
	s_mov_b32 m0, s26
	s_nop 0
	global_load_lds_dwordx4 v[176:177], off
	v_lshl_add_u64 v[176:177], s[0:1], 0, v[132:133]
	s_add_i32 m0, s26, 0x2000
	s_nop 0
	global_load_lds_dwordx4 v[176:177], off
	v_lshl_add_u64 v[176:177], v[238:239], 0, s[52:53]
	s_mov_b32 m0, s14
	s_nop 0
	global_load_lds_dwordx4 v[176:177], off
	v_lshl_add_u64 v[176:177], v[240:241], 0, s[52:53]
	s_mov_b32 m0, s15
	s_nop 0
	global_load_lds_dwordx4 v[176:177], off
	s_waitcnt vmcnt(8)
	s_waitcnt lgkmcnt(0)
	s_barrier
	s_setprio 1
	s_waitcnt lgkmcnt(0)
	v_mfma_f32_16x16x32_bf16 v[60:63], v[166:169], v[204:207], v[60:63]
	v_mfma_f32_16x16x32_bf16 v[56:59], v[180:183], v[204:207], v[56:59]
	v_mfma_f32_16x16x32_bf16 v[52:55], v[166:169], v[212:215], v[52:55]
	v_mfma_f32_16x16x32_bf16 v[44:47], v[180:183], v[212:215], v[44:47]
	v_mfma_f32_16x16x32_bf16 v[36:39], v[166:169], v[220:223], v[36:39]
	v_mfma_f32_16x16x32_bf16 v[28:31], v[180:183], v[220:223], v[28:31]
	v_mfma_f32_16x16x32_bf16 v[20:23], v[166:169], v[228:231], v[20:23]
	v_mfma_f32_16x16x32_bf16 v[12:15], v[180:183], v[228:231], v[12:15]
	v_mfma_f32_16x16x32_bf16 v[60:63], v[170:173], v[208:211], v[60:63]
	v_mfma_f32_16x16x32_bf16 v[56:59], v[184:187], v[208:211], v[56:59]
	v_mfma_f32_16x16x32_bf16 v[52:55], v[170:173], v[216:219], v[52:55]
	v_mfma_f32_16x16x32_bf16 v[44:47], v[184:187], v[216:219], v[44:47]
	v_mfma_f32_16x16x32_bf16 v[36:39], v[170:173], v[224:227], v[36:39]
	v_mfma_f32_16x16x32_bf16 v[28:31], v[184:187], v[224:227], v[28:31]
	v_mfma_f32_16x16x32_bf16 v[20:23], v[170:173], v[232:235], v[20:23]
	v_mfma_f32_16x16x32_bf16 v[12:15], v[184:187], v[232:235], v[12:15]
	s_setprio 0
	s_setprio 1
	v_mfma_f32_16x16x32_bf16 v[48:51], v[188:191], v[204:207], v[48:51]
	v_mfma_f32_16x16x32_bf16 v[40:43], v[196:199], v[204:207], v[40:43]
	v_mfma_f32_16x16x32_bf16 v[32:35], v[188:191], v[212:215], v[32:35]
	v_mfma_f32_16x16x32_bf16 v[24:27], v[196:199], v[212:215], v[24:27]
	v_mfma_f32_16x16x32_bf16 v[16:19], v[188:191], v[220:223], v[16:19]
	v_mfma_f32_16x16x32_bf16 v[8:11], v[196:199], v[220:223], v[8:11]
	v_mfma_f32_16x16x32_bf16 v[4:7], v[188:191], v[228:231], v[4:7]
	v_mfma_f32_16x16x32_bf16 v[0:3], v[196:199], v[228:231], v[0:3]
	v_mfma_f32_16x16x32_bf16 v[48:51], v[192:195], v[208:211], v[48:51]
	v_mfma_f32_16x16x32_bf16 v[40:43], v[200:203], v[208:211], v[40:43]
	v_mfma_f32_16x16x32_bf16 v[32:35], v[192:195], v[216:219], v[32:35]
	v_mfma_f32_16x16x32_bf16 v[24:27], v[200:203], v[216:219], v[24:27]
	v_mfma_f32_16x16x32_bf16 v[16:19], v[192:195], v[224:227], v[16:19]
	v_mfma_f32_16x16x32_bf16 v[8:11], v[200:203], v[224:227], v[8:11]
	v_mfma_f32_16x16x32_bf16 v[4:7], v[192:195], v[232:235], v[4:7]
	v_mfma_f32_16x16x32_bf16 v[0:3], v[200:203], v[232:235], v[0:3]
	s_setprio 0
	s_barrier
	s_add_i32 s25, s25, 2
	s_add_u32 vcc_lo, vcc_lo, 0x100
	s_addc_u32 vcc_hi, vcc_hi, 0
	s_add_u32 s23, s23, 0x100
	s_addc_u32 s24, s24, 0
	s_cmp_gt_u32 s25, 13
	s_cbranch_scc0 .LBB0_215
	s_branch .Lp1_kdone
	.p2align 6

; template <class Epi, class Sched, bool ALIGN_EPI = false, bool SP2 = false, bool ABLK = false>
; __device__ __forceinline__ void gemm_phase(PG8_LAS unsigned char* lds, const Gemm g, const Sched& S, const Epi& E) {
;     ...
;         const bool has_next = S.next(ui + 1, nxt);
;         const char* nA = has_next ? (const char*)g.A + (size_t)nxt.pm * tstepA : cA; const char* nB = has_next ? (const char*)g.Bt + (size_t)nxt.pn * tstep : cB;
;     ...
; #pragma unroll
;         for (int a = 0; a < 2; ++a)
; #pragma unroll
;             for (int b = 0; b < 2; ++b)
; #pragma unroll
;                 for (int m = 0; m < 4; ++m)
; #pragma unroll
;                     for (int n = 0; n < 2; ++n) acc[a][b][m][n] = (f32x4){0.f, 0.f, 0.f, 0.f};
.LBB0_480:
	s_ashr_i32 s27, s26, 31
	s_lshl_b64 s[30:31], s[26:27], 19
	s_add_u32 s30, s47, s30
	s_addc_u32 s31, s54, s31
	s_and_b64 s[36:37], s[34:35], exec
	s_cselect_b32 s15, s31, s39
	s_cselect_b32 s27, s30, s38
	s_ashr_i32 s29, s28, 31
	s_lshl_b64 s[36:37], s[28:29], 19
	s_add_u32 s36, s72, s36
	s_addc_u32 s37, s73, s37
	s_and_b64 s[42:43], s[34:35], exec
	s_cselect_b32 s29, s37, s41
	s_cselect_b32 s48, s36, s40
	s_lshl_b32 s16, s16, 8
	v_add_u32_e32 v2, s16, v184
	s_waitcnt lgkmcnt(0)
	v_ashrrev_i32_e32 v3, 31, v2
	v_lshl_add_u64 v[132:133], v[2:3], 2, s[86:87]
	v_mov_b32_e32 v2, v1
	v_mov_b32_e32 v3, v1
	s_add_u32 s49, s40, 0x100
	v_mov_b32_e32 v0, v1
	v_mov_b64_e32 v[6:7], v[2:3]
	v_mov_b64_e32 v[10:11], v[2:3]
	v_mov_b64_e32 v[22:23], v[2:3]
	v_mov_b64_e32 v[26:27], v[2:3]
	v_mov_b64_e32 v[38:39], v[2:3]
	v_mov_b64_e32 v[42:43], v[2:3]
	v_mov_b64_e32 v[54:55], v[2:3]
	v_mov_b64_e32 v[58:59], v[2:3]
	v_mov_b64_e32 v[14:15], v[2:3]
	v_mov_b64_e32 v[18:19], v[2:3]
	v_mov_b64_e32 v[30:31], v[2:3]
	v_mov_b64_e32 v[34:35], v[2:3]
	v_mov_b64_e32 v[46:47], v[2:3]
	v_mov_b64_e32 v[50:51], v[2:3]
	v_mov_b64_e32 v[62:63], v[2:3]
	v_mov_b64_e32 v[66:67], v[2:3]
	v_mov_b64_e32 v[70:71], v[2:3]
	v_mov_b64_e32 v[74:75], v[2:3]
	v_mov_b64_e32 v[86:87], v[2:3]
	v_mov_b64_e32 v[90:91], v[2:3]
	v_mov_b64_e32 v[102:103], v[2:3]
	v_mov_b64_e32 v[106:107], v[2:3]
	v_mov_b64_e32 v[118:119], v[2:3]
	v_mov_b64_e32 v[122:123], v[2:3]
	v_mov_b64_e32 v[78:79], v[2:3]
	v_mov_b64_e32 v[82:83], v[2:3]
	v_mov_b64_e32 v[94:95], v[2:3]
	v_mov_b64_e32 v[98:99], v[2:3]
	v_mov_b64_e32 v[110:111], v[2:3]
	v_mov_b64_e32 v[114:115], v[2:3]
	v_mov_b64_e32 v[126:127], v[2:3]
	v_mov_b64_e32 v[130:131], v[2:3]
	v_lshl_add_u64 v[134:135], s[38:39], 0, v[164:165]
	v_lshl_add_u64 v[136:137], s[38:39], 0, v[166:167]
	s_addc_u32 s81, s41, 0
	s_mov_b32 s82, -2
	s_mov_b64 s[40:41], 0
	v_mov_b64_e32 v[4:5], v[0:1]
	v_mov_b64_e32 v[8:9], v[0:1]
	v_mov_b64_e32 v[20:21], v[0:1]
	v_mov_b64_e32 v[24:25], v[0:1]
	v_mov_b64_e32 v[36:37], v[0:1]
	v_mov_b64_e32 v[40:41], v[0:1]
	v_mov_b64_e32 v[52:53], v[0:1]
	v_mov_b64_e32 v[56:57], v[0:1]
	v_mov_b64_e32 v[12:13], v[0:1]
	v_mov_b64_e32 v[16:17], v[0:1]
	v_mov_b64_e32 v[28:29], v[0:1]
	v_mov_b64_e32 v[32:33], v[0:1]
	v_mov_b64_e32 v[44:45], v[0:1]
	v_mov_b64_e32 v[48:49], v[0:1]
	v_mov_b64_e32 v[60:61], v[0:1]
	v_mov_b64_e32 v[64:65], v[0:1]
	v_mov_b64_e32 v[68:69], v[0:1]
	v_mov_b64_e32 v[72:73], v[0:1]
	v_mov_b64_e32 v[84:85], v[0:1]
	v_mov_b64_e32 v[88:89], v[0:1]
	v_mov_b64_e32 v[100:101], v[0:1]
	v_mov_b64_e32 v[104:105], v[0:1]
	v_mov_b64_e32 v[116:117], v[0:1]
	v_mov_b64_e32 v[120:121], v[0:1]
	v_mov_b64_e32 v[76:77], v[0:1]
	v_mov_b64_e32 v[80:81], v[0:1]
	v_mov_b64_e32 v[92:93], v[0:1]
	v_mov_b64_e32 v[96:97], v[0:1]
	v_mov_b64_e32 v[108:109], v[0:1]
	v_mov_b64_e32 v[112:113], v[0:1]
	v_mov_b64_e32 v[124:125], v[0:1]
	v_mov_b64_e32 v[128:129], v[0:1]
	s_branch .LBB0_482
	.p2align 6

; #define PG8_STAGE(bufoff, gbase, voff) do { _Pragma("unroll") for (int _i = 0; _i < 2; ++_i) \
;         __builtin_amdgcn_global_load_lds((const unsigned*)((const char*)(gbase) + (voff)[_i]), (PG8_LAS unsigned*)(lds + (bufoff) + ldsw + _i * 8192), 16, 0, 0); } while (0)
; #define PG8_LDA(dst, b, h) do { _Pragma("unroll") for (int m = 0; m < 4; ++m) _Pragma("unroll") for (int k = 0; k < 2; ++k) dst[m][k] = *(const PG8_LAS bf16x8*)(lds + PG8_SA(b, h) + aoff + m * 2048 + k * 1024); } while (0)
; #define PG8_LDB(dst, b, h) do { _Pragma("unroll") for (int n = 0; n < 2; ++n) _Pragma("unroll") for (int k = 0; k < 2; ++k) dst[n][k] = *(const PG8_LAS bf16x8*)(lds + PG8_SB(b, h) + boff + n * 2048 + k * 1024); } while (0)
; #define PG8_WAIT_V(n) asm volatile("s_waitcnt vmcnt(" #n ")" ::: "memory")
; #define PG8_WAIT_L(n) asm volatile("s_waitcnt lgkmcnt(" #n ")" ::: "memory")
; template <class Epi, class Sched, bool ALIGN_EPI = false, bool SP2 = false, bool ABLK = false>
; __device__ __forceinline__ void gemm_phase(PG8_LAS unsigned char* lds, const Gemm g, const Sched& S, const Epi& E) {
;     ...
;         const bool has_next = S.next(ui + 1, nxt);
;         const char* nA = has_next ? (const char*)g.A + (size_t)nxt.pm * tstepA : cA; const char* nB = has_next ? (const char*)g.Bt + (size_t)nxt.pn * tstep : cB;
;         for (int t = 0; t < nt; t += 2) {
;             if constexpr (Epi::MID) { if (t == nt / 2) E.mid(acc, cur, wr, wc, fr, fq); }
;             const bool last = (t == nt - 2);
;             const char* a1 = cA + (size_t)(t + 1) * kstepA;
;             const char* a2 = last ? nA : cA + (size_t)(t + 2) * kstepA; const char* b2 = last ? nB : cB + (size_t)(t + 2) * kstep;
;             const char* a3 = a2 + kstepA; const char* b3 = b2 + kstep;
;             if (last && has_next) S.a_ready(nxt);
;             if constexpr (SP2) {
;             PG8_LDB(B0, 0, 0); PG8_LDB(B1, 0, 1); PG8_SCHED; PG8_LDA(At, 0, 0); PG8_STAGE(PG8_SA(1, 1), a1 + hstepA, voffA);
;             PG8_WAIT_V(8); PG8_WAIT_L(0); PG8_BAR; PG8_MMA(0, 0, At, B0); PG8_MMA(0, 1, At, B1); PG8_BAR; PG8_SCHED;
;             PG8_LDA(At, 0, 1); PG8_STAGE(PG8_SB(0, 0), b2, voffB); PG8_STAGE(PG8_SB(0, 1), b2 + hstep, voffB); PG8_STAGE(PG8_SA(0, 0), a2, voffA);
;             PG8_WAIT_V(8); PG8_WAIT_L(0); PG8_BAR; PG8_MMA(1, 0, At, B0); PG8_MMA(1, 1, At, B1); PG8_BAR; PG8_SCHED;
.LBB0_533:
	s_ashr_i32 s21, s20, 31
	s_lshl_b64 s[8:9], s[20:21], 19
	s_add_u32 s24, s10, s8
	s_addc_u32 s25, s11, s9
	s_and_b64 s[8:9], s[26:27], exec
	s_cselect_b32 s7, s25, s37
	s_cselect_b32 s21, s24, s36
	s_ashr_i32 s23, s22, 31
	s_lshl_b64 s[8:9], s[22:23], 19
	s_add_u32 s28, s52, s8
	s_addc_u32 s29, s53, s9
	s_and_b64 s[8:9], s[26:27], exec
	s_cselect_b32 s23, s29, s35
	s_cselect_b32 s31, s28, s34
	s_add_u32 s61, s34, 0x100
	s_addc_u32 s62, s35, 0
	s_add_u32 s8, s36, 0xc000
	s_addc_u32 s9, s37, 0
	s_mov_b32 s63, -2
	ds_read_b128 v[128:131], v143
	ds_read_b128 v[176:179], v143 offset:1024
	ds_read_b128 v[180:183], v143 offset:2048
	ds_read_b128 v[184:187], v143 offset:3072
	ds_read_b128 v[188:191], v167
	ds_read_b128 v[192:195], v167 offset:1024
	ds_read_b128 v[196:199], v167 offset:2048
	ds_read_b128 v[200:203], v167 offset:3072
	s_add_u32 s2, s8, 0x4000
	s_addc_u32 s34, s9, 0
	s_cmp_eq_u32 s63, 12
	s_cselect_b32 s38, s21, s2
	s_cselect_b32 s39, s7, s34
	s_cselect_b32 s36, s31, s61
	s_cselect_b32 s37, s23, s62
	s_add_u32 s34, s38, 0x8000
	s_addc_u32 s35, s39, 0
	s_mov_b32 m0, s58
	v_lshl_add_u64 v[172:173], s[8:9], 0, v[162:163]
	ds_read_b128 v[204:207], v168
	ds_read_b128 v[208:211], v168 offset:1024
	ds_read_b128 v[212:215], v168 offset:2048
	ds_read_b128 v[216:219], v168 offset:3072
	ds_read_b128 v[220:223], v168 offset:4096
	ds_read_b128 v[224:227], v168 offset:5120
	ds_read_b128 v[228:231], v168 offset:6144
	ds_read_b128 v[232:235], v168 offset:7168
	global_load_lds_dwordx4 v[172:173], off
	v_lshl_add_u64 v[172:173], s[8:9], 0, v[164:165]
	s_mov_b32 m0, s59
	s_nop 0
	global_load_lds_dwordx4 v[172:173], off
	s_waitcnt vmcnt(8)
	s_waitcnt lgkmcnt(0)
	s_barrier
	s_setprio 1
	s_waitcnt lgkmcnt(0)
	v_mfma_f32_16x16x32_bf16 v[124:127], v[128:131], v[204:207], 0
	v_mfma_f32_16x16x32_bf16 v[120:123], v[180:183], v[204:207], 0
	v_mfma_f32_16x16x32_bf16 v[108:111], v[128:131], v[212:215], 0
	v_mfma_f32_16x16x32_bf16 v[104:107], v[180:183], v[212:215], 0
	v_mfma_f32_16x16x32_bf16 v[92:95], v[128:131], v[220:223], 0
	v_mfma_f32_16x16x32_bf16 v[88:91], v[180:183], v[220:223], 0
	v_mfma_f32_16x16x32_bf16 v[76:79], v[128:131], v[228:231], 0
	v_mfma_f32_16x16x32_bf16 v[72:75], v[180:183], v[228:231], 0
	v_mfma_f32_16x16x32_bf16 v[124:127], v[176:179], v[208:211], v[124:127]
	v_mfma_f32_16x16x32_bf16 v[120:123], v[184:187], v[208:211], v[120:123]
	v_mfma_f32_16x16x32_bf16 v[108:111], v[176:179], v[216:219], v[108:111]
	v_mfma_f32_16x16x32_bf16 v[104:107], v[184:187], v[216:219], v[104:107]
	v_mfma_f32_16x16x32_bf16 v[92:95], v[176:179], v[224:227], v[92:95]
	v_mfma_f32_16x16x32_bf16 v[88:91], v[184:187], v[224:227], v[88:91]
	v_mfma_f32_16x16x32_bf16 v[76:79], v[176:179], v[232:235], v[76:79]
	v_mfma_f32_16x16x32_bf16 v[72:75], v[184:187], v[232:235], v[72:75]
	s_setprio 0
	s_setprio 1
	v_mfma_f32_16x16x32_bf16 v[116:119], v[188:191], v[204:207], 0
	v_mfma_f32_16x16x32_bf16 v[112:115], v[196:199], v[204:207], 0
	v_mfma_f32_16x16x32_bf16 v[100:103], v[188:191], v[212:215], 0
	v_mfma_f32_16x16x32_bf16 v[96:99], v[196:199], v[212:215], 0
	v_mfma_f32_16x16x32_bf16 v[84:87], v[188:191], v[220:223], 0
	v_mfma_f32_16x16x32_bf16 v[80:83], v[196:199], v[220:223], 0
	v_mfma_f32_16x16x32_bf16 v[68:71], v[188:191], v[228:231], 0
	v_mfma_f32_16x16x32_bf16 v[64:67], v[196:199], v[228:231], 0
	v_mfma_f32_16x16x32_bf16 v[116:119], v[192:195], v[208:211], v[116:119]
	v_mfma_f32_16x16x32_bf16 v[112:115], v[200:203], v[208:211], v[112:115]
	v_mfma_f32_16x16x32_bf16 v[100:103], v[192:195], v[216:219], v[100:103]
	v_mfma_f32_16x16x32_bf16 v[96:99], v[200:203], v[216:219], v[96:99]
	v_mfma_f32_16x16x32_bf16 v[84:87], v[192:195], v[224:227], v[84:87]
	v_mfma_f32_16x16x32_bf16 v[80:83], v[200:203], v[224:227], v[80:83]
	v_mfma_f32_16x16x32_bf16 v[68:71], v[192:195], v[232:235], v[68:71]
	v_mfma_f32_16x16x32_bf16 v[64:67], v[200:203], v[232:235], v[64:67]
	s_setprio 0
	s_barrier
	s_mov_b32 m0, s60
	v_lshl_add_u64 v[172:173], s[36:37], 0, v[136:137]
	ds_read_b128 v[204:207], v168 offset:16384
	ds_read_b128 v[208:211], v168 offset:17408
	ds_read_b128 v[212:215], v168 offset:18432
	ds_read_b128 v[216:219], v168 offset:19456
	ds_read_b128 v[220:223], v168 offset:20480
	ds_read_b128 v[224:227], v168 offset:21504
	ds_read_b128 v[228:231], v168 offset:22528
	ds_read_b128 v[232:235], v168 offset:23552
	global_load_lds_dwordx4 v[172:173], off
	s_add_i32 m0, s60, 0x2000
	s_add_u32 s70, s36, 0x40000
	v_lshl_add_u64 v[236:237], s[36:37], 0, v[132:133]
	s_addc_u32 s71, s37, 0
	s_add_i32 s2, s57, s3
	global_load_lds_dwordx4 v[236:237], off
	v_lshl_add_u64 v[238:239], s[70:71], 0, v[136:137]
	s_mov_b32 m0, s2
	s_nop 0
	global_load_lds_dwordx4 v[238:239], off
	v_lshl_add_u64 v[238:239], s[70:71], 0, v[132:133]
	s_add_i32 m0, s2, 0x2000
	s_nop 0
	global_load_lds_dwordx4 v[238:239], off
	v_lshl_add_u64 v[238:239], s[38:39], 0, v[138:139]
	s_mov_b32 m0, s40
	s_nop 0
	global_load_lds_dwordx4 v[238:239], off
	v_lshl_add_u64 v[238:239], s[38:39], 0, v[134:135]
	s_mov_b32 m0, s41
	s_nop 0
	global_load_lds_dwordx4 v[238:239], off
	s_waitcnt vmcnt(8)
	s_waitcnt lgkmcnt(0)
	s_barrier
; #define PG8_STAGE(bufoff, gbase, voff) do { _Pragma("unroll") for (int _i = 0; _i < 2; ++_i) \
;         __builtin_amdgcn_global_load_lds((const unsigned*)((const char*)(gbase) + (voff)[_i]), (PG8_LAS unsigned*)(lds + (bufoff) + ldsw + _i * 8192), 16, 0, 0); } while (0)
; #define PG8_LDA(dst, b, h) do { _Pragma("unroll") for (int m = 0; m < 4; ++m) _Pragma("unroll") for (int k = 0; k < 2; ++k) dst[m][k] = *(const PG8_LAS bf16x8*)(lds + PG8_SA(b, h) + aoff + m * 2048 + k * 1024); } while (0)
; #define PG8_LDB(dst, b, h) do { _Pragma("unroll") for (int n = 0; n < 2; ++n) _Pragma("unroll") for (int k = 0; k < 2; ++k) dst[n][k] = *(const PG8_LAS bf16x8*)(lds + PG8_SB(b, h) + boff + n * 2048 + k * 1024); } while (0)
; #define PG8_MMA(ai, bj, At, Bt) do { __builtin_amdgcn_s_setprio(1); _Pragma("unroll") for (int m = 0; m < 4; ++m) _Pragma("unroll") for (int n = 0; n < 2; ++n) _Pragma("unroll") for (int k = 0; k < 2; ++k) \
;         acc[ai][bj][m][n] = __builtin_amdgcn_mfma_f32_16x16x32_bf16(Bt[n][k], At[m][k], acc[ai][bj][m][n], 0, 0, 0); __builtin_amdgcn_s_setprio(0); } while (0)
; #define PG8_WAIT_V(n) asm volatile("s_waitcnt vmcnt(" #n ")" ::: "memory")
; #define PG8_WAIT_L(n) asm volatile("s_waitcnt lgkmcnt(" #n ")" ::: "memory")
; #define PG8_BAR __builtin_amdgcn_s_barrier()
; #define PG8_SCHED __builtin_amdgcn_sched_barrier(0)
; template <class Epi, class Sched, bool ALIGN_EPI = false, bool SP2 = false, bool ABLK = false>
; __device__ __forceinline__ void gemm_phase(PG8_LAS unsigned char* lds, const Gemm g, const Sched& S, const Epi& E) {
;     ...
;             PG8_WAIT_V(8); PG8_WAIT_L(0); PG8_BAR; PG8_MMA(1, 0, At, B0); PG8_MMA(1, 1, At, B1); PG8_BAR; PG8_SCHED;
;             PG8_LDB(B0, 1, 0); PG8_LDB(B1, 1, 1); PG8_SCHED; PG8_LDA(At, 1, 0); PG8_STAGE(PG8_SA(0, 1), a2 + hstepA, voffA);
;             PG8_WAIT_V(8); PG8_WAIT_L(0); PG8_BAR; PG8_MMA(0, 0, At, B0); PG8_MMA(0, 1, At, B1); PG8_BAR; PG8_SCHED;
	s_setprio 1
	s_waitcnt lgkmcnt(0)
	v_mfma_f32_16x16x32_bf16 v[60:63], v[128:131], v[204:207], 0
	v_mfma_f32_16x16x32_bf16 v[56:59], v[180:183], v[204:207], 0
	v_mfma_f32_16x16x32_bf16 v[44:47], v[128:131], v[212:215], 0
	v_mfma_f32_16x16x32_bf16 v[40:43], v[180:183], v[212:215], 0
	v_mfma_f32_16x16x32_bf16 v[28:31], v[128:131], v[220:223], 0
	v_mfma_f32_16x16x32_bf16 v[24:27], v[180:183], v[220:223], 0
	v_mfma_f32_16x16x32_bf16 v[12:15], v[128:131], v[228:231], 0
	v_mfma_f32_16x16x32_bf16 v[8:11], v[180:183], v[228:231], 0
	v_mfma_f32_16x16x32_bf16 v[60:63], v[176:179], v[208:211], v[60:63]
	v_mfma_f32_16x16x32_bf16 v[56:59], v[184:187], v[208:211], v[56:59]
	v_mfma_f32_16x16x32_bf16 v[44:47], v[176:179], v[216:219], v[44:47]
	v_mfma_f32_16x16x32_bf16 v[40:43], v[184:187], v[216:219], v[40:43]
	v_mfma_f32_16x16x32_bf16 v[28:31], v[176:179], v[224:227], v[28:31]
	v_mfma_f32_16x16x32_bf16 v[24:27], v[184:187], v[224:227], v[24:27]
	v_mfma_f32_16x16x32_bf16 v[12:15], v[176:179], v[232:235], v[12:15]
	v_mfma_f32_16x16x32_bf16 v[8:11], v[184:187], v[232:235], v[8:11]
	s_setprio 0
	s_setprio 1
	v_mfma_f32_16x16x32_bf16 v[52:55], v[188:191], v[204:207], 0
	v_mfma_f32_16x16x32_bf16 v[48:51], v[196:199], v[204:207], 0
	v_mfma_f32_16x16x32_bf16 v[36:39], v[188:191], v[212:215], 0
	v_mfma_f32_16x16x32_bf16 v[32:35], v[196:199], v[212:215], 0
	v_mfma_f32_16x16x32_bf16 v[20:23], v[188:191], v[220:223], 0
	v_mfma_f32_16x16x32_bf16 v[16:19], v[196:199], v[220:223], 0
	v_mfma_f32_16x16x32_bf16 v[4:7], v[188:191], v[228:231], 0
	v_mfma_f32_16x16x32_bf16 v[0:3], v[196:199], v[228:231], 0
	v_mfma_f32_16x16x32_bf16 v[52:55], v[192:195], v[208:211], v[52:55]
	v_mfma_f32_16x16x32_bf16 v[48:51], v[200:203], v[208:211], v[48:51]
	v_mfma_f32_16x16x32_bf16 v[36:39], v[192:195], v[216:219], v[36:39]
	v_mfma_f32_16x16x32_bf16 v[32:35], v[200:203], v[216:219], v[32:35]
	v_mfma_f32_16x16x32_bf16 v[20:23], v[192:195], v[224:227], v[20:23]
	v_mfma_f32_16x16x32_bf16 v[16:19], v[200:203], v[224:227], v[16:19]
	v_mfma_f32_16x16x32_bf16 v[4:7], v[192:195], v[232:235], v[4:7]
	v_mfma_f32_16x16x32_bf16 v[0:3], v[200:203], v[232:235], v[0:3]
	s_setprio 0
	s_barrier
	s_add_i32 s2, 0, 0x18000
	v_add_u32_e32 v171, s2, v166
	s_add_i32 s70, 0, 0x1c000
	ds_read_b128 v[128:131], v171
	ds_read_b128 v[176:179], v171 offset:1024
	ds_read_b128 v[180:183], v171 offset:2048
	ds_read_b128 v[184:187], v171 offset:3072
	v_add_u32_e32 v171, s70, v166
	ds_read_b128 v[188:191], v171
	ds_read_b128 v[192:195], v171 offset:1024
	ds_read_b128 v[196:199], v171 offset:2048
	ds_read_b128 v[200:203], v171 offset:3072
	s_add_u32 s38, s38, 0x4000
	s_addc_u32 s39, s39, 0
	s_mov_b32 m0, s44
	v_lshl_add_u64 v[238:239], s[38:39], 0, v[138:139]
	ds_read_b128 v[204:207], v168 offset:32768
	ds_read_b128 v[208:211], v168 offset:33792
	ds_read_b128 v[212:215], v168 offset:34816
	ds_read_b128 v[216:219], v168 offset:35840
	ds_read_b128 v[220:223], v168 offset:36864
	ds_read_b128 v[224:227], v168 offset:37888
	ds_read_b128 v[228:231], v168 offset:38912
	ds_read_b128 v[232:235], v168 offset:39936
	global_load_lds_dwordx4 v[238:239], off
	v_lshl_add_u64 v[238:239], s[38:39], 0, v[134:135]
	s_mov_b32 m0, s45
	s_nop 0
	global_load_lds_dwordx4 v[238:239], off
	s_waitcnt vmcnt(8)
	s_waitcnt lgkmcnt(0)
	s_barrier
	s_setprio 1
	s_waitcnt lgkmcnt(0)
	v_mfma_f32_16x16x32_bf16 v[124:127], v[128:131], v[204:207], v[124:127]
	v_mfma_f32_16x16x32_bf16 v[120:123], v[180:183], v[204:207], v[120:123]
	v_mfma_f32_16x16x32_bf16 v[108:111], v[128:131], v[212:215], v[108:111]
	v_mfma_f32_16x16x32_bf16 v[104:107], v[180:183], v[212:215], v[104:107]
	v_mfma_f32_16x16x32_bf16 v[92:95], v[128:131], v[220:223], v[92:95]
	v_mfma_f32_16x16x32_bf16 v[88:91], v[180:183], v[220:223], v[88:91]
	v_mfma_f32_16x16x32_bf16 v[76:79], v[128:131], v[228:231], v[76:79]
	v_mfma_f32_16x16x32_bf16 v[72:75], v[180:183], v[228:231], v[72:75]
	v_mfma_f32_16x16x32_bf16 v[124:127], v[176:179], v[208:211], v[124:127]
	v_mfma_f32_16x16x32_bf16 v[120:123], v[184:187], v[208:211], v[120:123]
	v_mfma_f32_16x16x32_bf16 v[108:111], v[176:179], v[216:219], v[108:111]
	v_mfma_f32_16x16x32_bf16 v[104:107], v[184:187], v[216:219], v[104:107]
	v_mfma_f32_16x16x32_bf16 v[92:95], v[176:179], v[224:227], v[92:95]
	v_mfma_f32_16x16x32_bf16 v[88:91], v[184:187], v[224:227], v[88:91]
	v_mfma_f32_16x16x32_bf16 v[76:79], v[176:179], v[232:235], v[76:79]
	v_mfma_f32_16x16x32_bf16 v[72:75], v[184:187], v[232:235], v[72:75]
	s_setprio 0
	s_setprio 1
	v_mfma_f32_16x16x32_bf16 v[116:119], v[188:191], v[204:207], v[116:119]
	v_mfma_f32_16x16x32_bf16 v[112:115], v[196:199], v[204:207], v[112:115]
	v_mfma_f32_16x16x32_bf16 v[100:103], v[188:191], v[212:215], v[100:103]
	v_mfma_f32_16x16x32_bf16 v[96:99], v[196:199], v[212:215], v[96:99]
	v_mfma_f32_16x16x32_bf16 v[84:87], v[188:191], v[220:223], v[84:87]
	v_mfma_f32_16x16x32_bf16 v[80:83], v[196:199], v[220:223], v[80:83]
	v_mfma_f32_16x16x32_bf16 v[68:71], v[188:191], v[228:231], v[68:71]
	v_mfma_f32_16x16x32_bf16 v[64:67], v[196:199], v[228:231], v[64:67]
	v_mfma_f32_16x16x32_bf16 v[116:119], v[192:195], v[208:211], v[116:119]
	v_mfma_f32_16x16x32_bf16 v[112:115], v[200:203], v[208:211], v[112:115]
	v_mfma_f32_16x16x32_bf16 v[100:103], v[192:195], v[216:219], v[100:103]
	v_mfma_f32_16x16x32_bf16 v[96:99], v[200:203], v[216:219], v[96:99]
	v_mfma_f32_16x16x32_bf16 v[84:87], v[192:195], v[224:227], v[84:87]
	v_mfma_f32_16x16x32_bf16 v[80:83], v[200:203], v[224:227], v[80:83]
	v_mfma_f32_16x16x32_bf16 v[68:71], v[192:195], v[232:235], v[68:71]
	v_mfma_f32_16x16x32_bf16 v[64:67], v[200:203], v[232:235], v[64:67]
	s_setprio 0
	s_barrier
; #define PG8_STAGE(bufoff, gbase, voff) do { _Pragma("unroll") for (int _i = 0; _i < 2; ++_i) \
;         __builtin_amdgcn_global_load_lds((const unsigned*)((const char*)(gbase) + (voff)[_i]), (PG8_LAS unsigned*)(lds + (bufoff) + ldsw + _i * 8192), 16, 0, 0); } while (0)
; #define PG8_LDA(dst, b, h) do { _Pragma("unroll") for (int m = 0; m < 4; ++m) _Pragma("unroll") for (int k = 0; k < 2; ++k) dst[m][k] = *(const PG8_LAS bf16x8*)(lds + PG8_SA(b, h) + aoff + m * 2048 + k * 1024); } while (0)
; #define PG8_LDB(dst, b, h) do { _Pragma("unroll") for (int n = 0; n < 2; ++n) _Pragma("unroll") for (int k = 0; k < 2; ++k) dst[n][k] = *(const PG8_LAS bf16x8*)(lds + PG8_SB(b, h) + boff + n * 2048 + k * 1024); } while (0)
; #define PG8_MMA(ai, bj, At, Bt) do { __builtin_amdgcn_s_setprio(1); _Pragma("unroll") for (int m = 0; m < 4; ++m) _Pragma("unroll") for (int n = 0; n < 2; ++n) _Pragma("unroll") for (int k = 0; k < 2; ++k) \
;         acc[ai][bj][m][n] = __builtin_amdgcn_mfma_f32_16x16x32_bf16(Bt[n][k], At[m][k], acc[ai][bj][m][n], 0, 0, 0); __builtin_amdgcn_s_setprio(0); } while (0)
; #define PG8_WAIT_V(n) asm volatile("s_waitcnt vmcnt(" #n ")" ::: "memory")
; #define PG8_WAIT_L(n) asm volatile("s_waitcnt lgkmcnt(" #n ")" ::: "memory")
; #define PG8_BAR __builtin_amdgcn_s_barrier()
; #define PG8_SCHED __builtin_amdgcn_sched_barrier(0)
; template <class Epi, class Sched, bool ALIGN_EPI = false, bool SP2 = false, bool ABLK = false>
; __device__ __forceinline__ void gemm_phase(PG8_LAS unsigned char* lds, const Gemm g, const Sched& S, const Epi& E) {
;     ...
;             PG8_LDB(B0, 1, 0); PG8_LDB(B1, 1, 1); PG8_SCHED; PG8_LDA(At, 1, 0); PG8_STAGE(PG8_SA(0, 1), a2 + hstepA, voffA);
;             PG8_WAIT_V(8); PG8_WAIT_L(0); PG8_BAR; PG8_MMA(0, 0, At, B0); PG8_MMA(0, 1, At, B1); PG8_BAR; PG8_SCHED;
;             PG8_LDA(At, 1, 1); PG8_STAGE(PG8_SB(1, 0), b3, voffB); PG8_STAGE(PG8_SB(1, 1), b3 + hstep, voffB); PG8_STAGE(PG8_SA(1, 0), a3, voffA);
;             PG8_WAIT_V(8); PG8_WAIT_L(0); PG8_BAR; PG8_MMA(1, 0, At, B0); PG8_MMA(1, 1, At, B1); PG8_BAR; PG8_SCHED;
	s_add_i32 s2, s2, s3
	v_lshl_add_u64 v[172:173], v[172:173], 0, s[16:17]
	s_mov_b32 m0, s2
	ds_read_b128 v[204:207], v168 offset:49152
	ds_read_b128 v[208:211], v168 offset:50176
	ds_read_b128 v[212:215], v168 offset:51200
	ds_read_b128 v[216:219], v168 offset:52224
	ds_read_b128 v[220:223], v168 offset:53248
	ds_read_b128 v[224:227], v168 offset:54272
	ds_read_b128 v[228:231], v168 offset:55296
	ds_read_b128 v[232:235], v168 offset:56320
	global_load_lds_dwordx4 v[172:173], off
	s_add_i32 m0, s2, 0x2000
	s_add_u32 s36, s36, 0x40080
	v_lshl_add_u64 v[172:173], v[236:237], 0, s[16:17]
	s_addc_u32 s37, s37, 0
	s_add_i32 s2, s70, s3
	global_load_lds_dwordx4 v[172:173], off
	v_lshl_add_u64 v[172:173], s[36:37], 0, v[136:137]
	s_mov_b32 m0, s2
	s_nop 0
	global_load_lds_dwordx4 v[172:173], off
	v_lshl_add_u64 v[172:173], s[36:37], 0, v[132:133]
	s_add_i32 m0, s2, 0x2000
	s_nop 0
	global_load_lds_dwordx4 v[172:173], off
	v_lshl_add_u64 v[172:173], s[34:35], 0, v[138:139]
	s_mov_b32 m0, s55
	s_nop 0
	global_load_lds_dwordx4 v[172:173], off
	v_lshl_add_u64 v[172:173], s[34:35], 0, v[134:135]
	s_mov_b32 m0, s56
	s_nop 0
	global_load_lds_dwordx4 v[172:173], off
	s_waitcnt vmcnt(8)
	s_waitcnt lgkmcnt(0)
	s_barrier
	s_setprio 1
	s_waitcnt lgkmcnt(0)
	v_mfma_f32_16x16x32_bf16 v[60:63], v[128:131], v[204:207], v[60:63]
	v_mfma_f32_16x16x32_bf16 v[56:59], v[180:183], v[204:207], v[56:59]
	v_mfma_f32_16x16x32_bf16 v[44:47], v[128:131], v[212:215], v[44:47]
	v_mfma_f32_16x16x32_bf16 v[40:43], v[180:183], v[212:215], v[40:43]
	v_mfma_f32_16x16x32_bf16 v[28:31], v[128:131], v[220:223], v[28:31]
	v_mfma_f32_16x16x32_bf16 v[24:27], v[180:183], v[220:223], v[24:27]
	v_mfma_f32_16x16x32_bf16 v[12:15], v[128:131], v[228:231], v[12:15]
	v_mfma_f32_16x16x32_bf16 v[8:11], v[180:183], v[228:231], v[8:11]
	v_mfma_f32_16x16x32_bf16 v[60:63], v[176:179], v[208:211], v[60:63]
	v_mfma_f32_16x16x32_bf16 v[56:59], v[184:187], v[208:211], v[56:59]
	v_mfma_f32_16x16x32_bf16 v[44:47], v[176:179], v[216:219], v[44:47]
	v_mfma_f32_16x16x32_bf16 v[40:43], v[184:187], v[216:219], v[40:43]
	v_mfma_f32_16x16x32_bf16 v[28:31], v[176:179], v[224:227], v[28:31]
	v_mfma_f32_16x16x32_bf16 v[24:27], v[184:187], v[224:227], v[24:27]
	v_mfma_f32_16x16x32_bf16 v[12:15], v[176:179], v[232:235], v[12:15]
	v_mfma_f32_16x16x32_bf16 v[8:11], v[184:187], v[232:235], v[8:11]
	s_setprio 0
	s_setprio 1
	v_mfma_f32_16x16x32_bf16 v[52:55], v[188:191], v[204:207], v[52:55]
	v_mfma_f32_16x16x32_bf16 v[48:51], v[196:199], v[204:207], v[48:51]
	v_mfma_f32_16x16x32_bf16 v[36:39], v[188:191], v[212:215], v[36:39]
	v_mfma_f32_16x16x32_bf16 v[32:35], v[196:199], v[212:215], v[32:35]
	v_mfma_f32_16x16x32_bf16 v[20:23], v[188:191], v[220:223], v[20:23]
	v_mfma_f32_16x16x32_bf16 v[16:19], v[196:199], v[220:223], v[16:19]
	v_mfma_f32_16x16x32_bf16 v[4:7], v[188:191], v[228:231], v[4:7]
	v_mfma_f32_16x16x32_bf16 v[0:3], v[196:199], v[228:231], v[0:3]
	v_mfma_f32_16x16x32_bf16 v[52:55], v[192:195], v[208:211], v[52:55]
	v_mfma_f32_16x16x32_bf16 v[48:51], v[200:203], v[208:211], v[48:51]
	v_mfma_f32_16x16x32_bf16 v[36:39], v[192:195], v[216:219], v[36:39]
	v_mfma_f32_16x16x32_bf16 v[32:35], v[200:203], v[216:219], v[32:35]
	v_mfma_f32_16x16x32_bf16 v[20:23], v[192:195], v[224:227], v[20:23]
	v_mfma_f32_16x16x32_bf16 v[16:19], v[200:203], v[224:227], v[16:19]
	v_mfma_f32_16x16x32_bf16 v[4:7], v[192:195], v[232:235], v[4:7]
	v_mfma_f32_16x16x32_bf16 v[0:3], v[200:203], v[232:235], v[0:3]
	s_setprio 0
	s_barrier
	s_add_i32 s63, s63, 2
	s_add_u32 s61, s61, 0x100
	s_addc_u32 s62, s62, 0
	s_add_u32 s8, s8, 0x10000
	s_addc_u32 s9, s9, 0
	s_cmp_gt_u32 s63, 13
	s_cbranch_scc0 .LBB0_534
	s_branch .Lp4_kdone
	.p2align 6

; #define PG8_STAGE(bufoff, gbase, voff) do { _Pragma("unroll") for (int _i = 0; _i < 2; ++_i) \
;         __builtin_amdgcn_global_load_lds((const unsigned*)((const char*)(gbase) + (voff)[_i]), (PG8_LAS unsigned*)(lds + (bufoff) + ldsw + _i * 8192), 16, 0, 0); } while (0)
; #define PG8_LDA(dst, b, h) do { _Pragma("unroll") for (int m = 0; m < 4; ++m) _Pragma("unroll") for (int k = 0; k < 2; ++k) dst[m][k] = *(const PG8_LAS bf16x8*)(lds + PG8_SA(b, h) + aoff + m * 2048 + k * 1024); } while (0)
; #define PG8_LDB(dst, b, h) do { _Pragma("unroll") for (int n = 0; n < 2; ++n) _Pragma("unroll") for (int k = 0; k < 2; ++k) dst[n][k] = *(const PG8_LAS bf16x8*)(lds + PG8_SB(b, h) + boff + n * 2048 + k * 1024); } while (0)
; #define PG8_WAIT_V(n) asm volatile("s_waitcnt vmcnt(" #n ")" ::: "memory")
; #define PG8_WAIT_L(n) asm volatile("s_waitcnt lgkmcnt(" #n ")" ::: "memory")
; template <class Epi, class Sched, bool ALIGN_EPI = false, bool SP2 = false, bool ABLK = false>
; __device__ __forceinline__ void gemm_phase(PG8_LAS unsigned char* lds, const Gemm g, const Sched& S, const Epi& E) {
;     ...
;         const bool has_next = S.next(ui + 1, nxt);
;         const char* nA = has_next ? (const char*)g.A + (size_t)nxt.pm * tstepA : cA; const char* nB = has_next ? (const char*)g.Bt + (size_t)nxt.pn * tstep : cB;
;         for (int t = 0; t < nt; t += 2) {
;             if constexpr (Epi::MID) { if (t == nt / 2) E.mid(acc, cur, wr, wc, fr, fq); }
;             const bool last = (t == nt - 2);
;             const char* a1 = cA + (size_t)(t + 1) * kstepA;
;             const char* a2 = last ? nA : cA + (size_t)(t + 2) * kstepA; const char* b2 = last ? nB : cB + (size_t)(t + 2) * kstep;
;             const char* a3 = a2 + kstepA; const char* b3 = b2 + kstep;
;             if (last && has_next) S.a_ready(nxt);
;             if constexpr (SP2) {
;             PG8_LDB(B0, 0, 0); PG8_LDB(B1, 0, 1); PG8_SCHED; PG8_LDA(At, 0, 0); PG8_STAGE(PG8_SA(1, 1), a1 + hstepA, voffA);
;             PG8_WAIT_V(8); PG8_WAIT_L(0); PG8_BAR; PG8_MMA(0, 0, At, B0); PG8_MMA(0, 1, At, B1); PG8_BAR; PG8_SCHED;
;             PG8_LDA(At, 0, 1); PG8_STAGE(PG8_SB(0, 0), b2, voffB); PG8_STAGE(PG8_SB(0, 1), b2 + hstep, voffB); PG8_STAGE(PG8_SA(0, 0), a2, voffA);
;             PG8_WAIT_V(8); PG8_WAIT_L(0); PG8_BAR; PG8_MMA(1, 0, At, B0); PG8_MMA(1, 1, At, B1); PG8_BAR; PG8_SCHED;
.LBB0_577:
	s_ashr_i32 s21, s20, 31
	s_lshl_b64 s[24:25], s[20:21], 21
	s_add_u32 s24, s42, s24
	s_addc_u32 s25, s43, s25
	s_and_b64 s[28:29], s[26:27], exec
	s_cselect_b32 s21, s25, s37
	s_cselect_b32 s31, s24, s36
	s_ashr_i32 s23, s22, 31
	s_lshl_b64 s[28:29], s[22:23], 21
	s_add_u32 s28, s50, s28
	s_addc_u32 s29, s51, s29
	s_and_b64 s[38:39], s[26:27], exec
	s_cselect_b32 s23, s29, s35
	s_cselect_b32 s61, s28, s34
	s_add_u32 s62, s34, 0x100
	s_addc_u32 s63, s35, 0
	s_add_u32 s34, s36, 0xc000
	s_addc_u32 s35, s37, 0
	s_mov_b32 s64, -2
	ds_read_b128 v[142:145], v151
	ds_read_b128 v[154:157], v151 offset:1024
	ds_read_b128 v[158:161], v151 offset:2048
	ds_read_b128 v[162:165], v151 offset:3072
	ds_read_b128 v[166:169], v152
	ds_read_b128 v[170:173], v152 offset:1024
	ds_read_b128 v[174:177], v152 offset:2048
	ds_read_b128 v[178:181], v152 offset:3072
	s_add_u32 s36, s34, 0x4000
	s_addc_u32 s37, s35, 0
	s_cmp_eq_u32 s64, 60
	s_cselect_b32 s40, s31, s36
	s_cselect_b32 s41, s21, s37
	s_cselect_b32 s38, s61, s62
	s_cselect_b32 s39, s23, s63
	s_add_u32 s36, s40, 0x8000
	s_addc_u32 s37, s41, 0
	v_lshl_add_u64 v[146:147], s[34:35], 0, v[138:139]
	s_add_i32 m0, s45, 0xc000
	ds_read_b128 v[182:185], v153
	ds_read_b128 v[186:189], v153 offset:1024
	ds_read_b128 v[190:193], v153 offset:2048
	ds_read_b128 v[194:197], v153 offset:3072
	ds_read_b128 v[198:201], v153 offset:4096
	ds_read_b128 v[202:205], v153 offset:5120
	ds_read_b128 v[206:209], v153 offset:6144
	ds_read_b128 v[210:213], v153 offset:7168
	global_load_lds_dwordx4 v[146:147], off
	v_lshl_add_u64 v[146:147], s[34:35], 0, v[140:141]
	s_add_i32 m0, s45, 0xe000
	s_nop 0
	global_load_lds_dwordx4 v[146:147], off
	s_waitcnt vmcnt(8)
	s_waitcnt lgkmcnt(0)
	s_barrier
	s_setprio 1
	s_waitcnt lgkmcnt(0)
	v_mfma_f32_16x16x32_bf16 v[124:127], v[142:145], v[182:185], 0
	v_mfma_f32_16x16x32_bf16 v[120:123], v[158:161], v[182:185], 0
	v_mfma_f32_16x16x32_bf16 v[116:119], v[142:145], v[190:193], 0
	v_mfma_f32_16x16x32_bf16 v[112:115], v[158:161], v[190:193], 0
	v_mfma_f32_16x16x32_bf16 v[96:99], v[142:145], v[198:201], 0
	v_mfma_f32_16x16x32_bf16 v[88:91], v[158:161], v[198:201], 0
	v_mfma_f32_16x16x32_bf16 v[80:83], v[142:145], v[206:209], 0
	v_mfma_f32_16x16x32_bf16 v[72:75], v[158:161], v[206:209], 0
	v_mfma_f32_16x16x32_bf16 v[124:127], v[154:157], v[186:189], v[124:127]
	v_mfma_f32_16x16x32_bf16 v[120:123], v[162:165], v[186:189], v[120:123]
	v_mfma_f32_16x16x32_bf16 v[116:119], v[154:157], v[194:197], v[116:119]
	v_mfma_f32_16x16x32_bf16 v[112:115], v[162:165], v[194:197], v[112:115]
	v_mfma_f32_16x16x32_bf16 v[96:99], v[154:157], v[202:205], v[96:99]
	v_mfma_f32_16x16x32_bf16 v[88:91], v[162:165], v[202:205], v[88:91]
	v_mfma_f32_16x16x32_bf16 v[80:83], v[154:157], v[210:213], v[80:83]
	v_mfma_f32_16x16x32_bf16 v[72:75], v[162:165], v[210:213], v[72:75]
	s_setprio 0
	s_setprio 1
	v_mfma_f32_16x16x32_bf16 v[108:111], v[166:169], v[182:185], 0
	v_mfma_f32_16x16x32_bf16 v[104:107], v[174:177], v[182:185], 0
	v_mfma_f32_16x16x32_bf16 v[100:103], v[166:169], v[190:193], 0
	v_mfma_f32_16x16x32_bf16 v[92:95], v[174:177], v[190:193], 0
	v_mfma_f32_16x16x32_bf16 v[84:87], v[166:169], v[198:201], 0
	v_mfma_f32_16x16x32_bf16 v[76:79], v[174:177], v[198:201], 0
	v_mfma_f32_16x16x32_bf16 v[68:71], v[166:169], v[206:209], 0
	v_mfma_f32_16x16x32_bf16 v[64:67], v[174:177], v[206:209], 0
	v_mfma_f32_16x16x32_bf16 v[108:111], v[170:173], v[186:189], v[108:111]
	v_mfma_f32_16x16x32_bf16 v[104:107], v[178:181], v[186:189], v[104:107]
	v_mfma_f32_16x16x32_bf16 v[100:103], v[170:173], v[194:197], v[100:103]
	v_mfma_f32_16x16x32_bf16 v[92:95], v[178:181], v[194:197], v[92:95]
	v_mfma_f32_16x16x32_bf16 v[84:87], v[170:173], v[202:205], v[84:87]
	v_mfma_f32_16x16x32_bf16 v[76:79], v[178:181], v[202:205], v[76:79]
	v_mfma_f32_16x16x32_bf16 v[68:71], v[170:173], v[210:213], v[68:71]
	v_mfma_f32_16x16x32_bf16 v[64:67], v[178:181], v[210:213], v[64:67]
	s_setprio 0
	s_barrier
	s_add_i32 s65, s56, s44
	v_lshl_add_u64 v[146:147], s[38:39], 0, v[132:133]
	s_mov_b32 m0, s65
	ds_read_b128 v[182:185], v153 offset:16384
	ds_read_b128 v[186:189], v153 offset:17408
	ds_read_b128 v[190:193], v153 offset:18432
	ds_read_b128 v[194:197], v153 offset:19456
	ds_read_b128 v[198:201], v153 offset:20480
	ds_read_b128 v[202:205], v153 offset:21504
	ds_read_b128 v[206:209], v153 offset:22528
	ds_read_b128 v[210:213], v153 offset:23552
	global_load_lds_dwordx4 v[146:147], off
	s_add_i32 m0, s65, 0x2000
	s_add_u32 s70, s38, 0x100000
	v_lshl_add_u64 v[214:215], s[38:39], 0, v[128:129]
	s_addc_u32 s71, s39, 0
	s_add_i32 s65, s57, s44
	global_load_lds_dwordx4 v[214:215], off
	v_lshl_add_u64 v[216:217], s[70:71], 0, v[132:133]
	s_mov_b32 m0, s65
	s_nop 0
	global_load_lds_dwordx4 v[216:217], off
	v_lshl_add_u64 v[216:217], s[70:71], 0, v[128:129]
	s_add_i32 m0, s65, 0x2000
	s_nop 0
	global_load_lds_dwordx4 v[216:217], off
	v_lshl_add_u64 v[216:217], s[40:41], 0, v[134:135]
	s_mov_b32 m0, s45
	s_nop 0
	global_load_lds_dwordx4 v[216:217], off
	v_lshl_add_u64 v[216:217], s[40:41], 0, v[130:131]
	s_mov_b32 m0, s47
	s_nop 0
	global_load_lds_dwordx4 v[216:217], off
	s_waitcnt vmcnt(8)
	s_waitcnt lgkmcnt(0)
	s_barrier
; #define PG8_STAGE(bufoff, gbase, voff) do { _Pragma("unroll") for (int _i = 0; _i < 2; ++_i) \
;         __builtin_amdgcn_global_load_lds((const unsigned*)((const char*)(gbase) + (voff)[_i]), (PG8_LAS unsigned*)(lds + (bufoff) + ldsw + _i * 8192), 16, 0, 0); } while (0)
; #define PG8_LDA(dst, b, h) do { _Pragma("unroll") for (int m = 0; m < 4; ++m) _Pragma("unroll") for (int k = 0; k < 2; ++k) dst[m][k] = *(const PG8_LAS bf16x8*)(lds + PG8_SA(b, h) + aoff + m * 2048 + k * 1024); } while (0)
; #define PG8_LDB(dst, b, h) do { _Pragma("unroll") for (int n = 0; n < 2; ++n) _Pragma("unroll") for (int k = 0; k < 2; ++k) dst[n][k] = *(const PG8_LAS bf16x8*)(lds + PG8_SB(b, h) + boff + n * 2048 + k * 1024); } while (0)
; #define PG8_MMA(ai, bj, At, Bt) do { __builtin_amdgcn_s_setprio(1); _Pragma("unroll") for (int m = 0; m < 4; ++m) _Pragma("unroll") for (int n = 0; n < 2; ++n) _Pragma("unroll") for (int k = 0; k < 2; ++k) \
;         acc[ai][bj][m][n] = __builtin_amdgcn_mfma_f32_16x16x32_bf16(Bt[n][k], At[m][k], acc[ai][bj][m][n], 0, 0, 0); __builtin_amdgcn_s_setprio(0); } while (0)
; #define PG8_WAIT_V(n) asm volatile("s_waitcnt vmcnt(" #n ")" ::: "memory")
; #define PG8_WAIT_L(n) asm volatile("s_waitcnt lgkmcnt(" #n ")" ::: "memory")
; #define PG8_BAR __builtin_amdgcn_s_barrier()
; #define PG8_SCHED __builtin_amdgcn_sched_barrier(0)
; template <class Epi, class Sched, bool ALIGN_EPI = false, bool SP2 = false, bool ABLK = false>
; __device__ __forceinline__ void gemm_phase(PG8_LAS unsigned char* lds, const Gemm g, const Sched& S, const Epi& E) {
;     ...
;             PG8_WAIT_V(8); PG8_WAIT_L(0); PG8_BAR; PG8_MMA(1, 0, At, B0); PG8_MMA(1, 1, At, B1); PG8_BAR; PG8_SCHED;
;             PG8_LDB(B0, 1, 0); PG8_LDB(B1, 1, 1); PG8_SCHED; PG8_LDA(At, 1, 0); PG8_STAGE(PG8_SA(0, 1), a2 + hstepA, voffA);
;             PG8_WAIT_V(8); PG8_WAIT_L(0); PG8_BAR; PG8_MMA(0, 0, At, B0); PG8_MMA(0, 1, At, B1); PG8_BAR; PG8_SCHED;
	s_setprio 1
	s_waitcnt lgkmcnt(0)
	v_mfma_f32_16x16x32_bf16 v[60:63], v[142:145], v[182:185], 0
	v_mfma_f32_16x16x32_bf16 v[56:59], v[158:161], v[182:185], 0
	v_mfma_f32_16x16x32_bf16 v[48:51], v[142:145], v[190:193], 0
	v_mfma_f32_16x16x32_bf16 v[40:43], v[158:161], v[190:193], 0
	v_mfma_f32_16x16x32_bf16 v[32:35], v[142:145], v[198:201], 0
	v_mfma_f32_16x16x32_bf16 v[24:27], v[158:161], v[198:201], 0
	v_mfma_f32_16x16x32_bf16 v[16:19], v[142:145], v[206:209], 0
	v_mfma_f32_16x16x32_bf16 v[8:11], v[158:161], v[206:209], 0
	v_mfma_f32_16x16x32_bf16 v[60:63], v[154:157], v[186:189], v[60:63]
	v_mfma_f32_16x16x32_bf16 v[56:59], v[162:165], v[186:189], v[56:59]
	v_mfma_f32_16x16x32_bf16 v[48:51], v[154:157], v[194:197], v[48:51]
	v_mfma_f32_16x16x32_bf16 v[40:43], v[162:165], v[194:197], v[40:43]
	v_mfma_f32_16x16x32_bf16 v[32:35], v[154:157], v[202:205], v[32:35]
	v_mfma_f32_16x16x32_bf16 v[24:27], v[162:165], v[202:205], v[24:27]
	v_mfma_f32_16x16x32_bf16 v[16:19], v[154:157], v[210:213], v[16:19]
	v_mfma_f32_16x16x32_bf16 v[8:11], v[162:165], v[210:213], v[8:11]
	s_setprio 0
	s_setprio 1
	v_mfma_f32_16x16x32_bf16 v[52:55], v[166:169], v[182:185], 0
	v_mfma_f32_16x16x32_bf16 v[44:47], v[174:177], v[182:185], 0
	v_mfma_f32_16x16x32_bf16 v[36:39], v[166:169], v[190:193], 0
	v_mfma_f32_16x16x32_bf16 v[28:31], v[174:177], v[190:193], 0
	v_mfma_f32_16x16x32_bf16 v[20:23], v[166:169], v[198:201], 0
	v_mfma_f32_16x16x32_bf16 v[12:15], v[174:177], v[198:201], 0
	v_mfma_f32_16x16x32_bf16 v[4:7], v[166:169], v[206:209], 0
	v_mfma_f32_16x16x32_bf16 v[0:3], v[174:177], v[206:209], 0
	v_mfma_f32_16x16x32_bf16 v[52:55], v[170:173], v[186:189], v[52:55]
	v_mfma_f32_16x16x32_bf16 v[44:47], v[178:181], v[186:189], v[44:47]
	v_mfma_f32_16x16x32_bf16 v[36:39], v[170:173], v[194:197], v[36:39]
	v_mfma_f32_16x16x32_bf16 v[28:31], v[178:181], v[194:197], v[28:31]
	v_mfma_f32_16x16x32_bf16 v[20:23], v[170:173], v[202:205], v[20:23]
	v_mfma_f32_16x16x32_bf16 v[12:15], v[178:181], v[202:205], v[12:15]
	v_mfma_f32_16x16x32_bf16 v[4:7], v[170:173], v[210:213], v[4:7]
	v_mfma_f32_16x16x32_bf16 v[0:3], v[178:181], v[210:213], v[0:3]
	s_setprio 0
	s_barrier
	s_add_i32 s65, 0, 0x18000
	v_add_u32_e32 v136, s65, v150
	s_add_i32 s68, 0, 0x1c000
	ds_read_b128 v[142:145], v136
	ds_read_b128 v[154:157], v136 offset:1024
	ds_read_b128 v[158:161], v136 offset:2048
	ds_read_b128 v[162:165], v136 offset:3072
	v_add_u32_e32 v136, s68, v150
	ds_read_b128 v[166:169], v136
	ds_read_b128 v[170:173], v136 offset:1024
	ds_read_b128 v[174:177], v136 offset:2048
	ds_read_b128 v[178:181], v136 offset:3072
	s_add_u32 s40, s40, 0x4000
	s_addc_u32 s41, s41, 0
	s_mov_b32 m0, s48
	v_lshl_add_u64 v[216:217], s[40:41], 0, v[134:135]
	ds_read_b128 v[182:185], v153 offset:32768
	ds_read_b128 v[186:189], v153 offset:33792
	ds_read_b128 v[190:193], v153 offset:34816
	ds_read_b128 v[194:197], v153 offset:35840
	ds_read_b128 v[198:201], v153 offset:36864
	ds_read_b128 v[202:205], v153 offset:37888
	ds_read_b128 v[206:209], v153 offset:38912
	ds_read_b128 v[210:213], v153 offset:39936
	global_load_lds_dwordx4 v[216:217], off
	v_lshl_add_u64 v[216:217], s[40:41], 0, v[130:131]
	s_mov_b32 m0, s49
	s_nop 0
	global_load_lds_dwordx4 v[216:217], off
	s_waitcnt vmcnt(8)
	s_waitcnt lgkmcnt(0)
	s_barrier
	s_setprio 1
	s_waitcnt lgkmcnt(0)
	v_mfma_f32_16x16x32_bf16 v[124:127], v[142:145], v[182:185], v[124:127]
	v_mfma_f32_16x16x32_bf16 v[120:123], v[158:161], v[182:185], v[120:123]
	v_mfma_f32_16x16x32_bf16 v[116:119], v[142:145], v[190:193], v[116:119]
	v_mfma_f32_16x16x32_bf16 v[112:115], v[158:161], v[190:193], v[112:115]
	v_mfma_f32_16x16x32_bf16 v[96:99], v[142:145], v[198:201], v[96:99]
	v_mfma_f32_16x16x32_bf16 v[88:91], v[158:161], v[198:201], v[88:91]
	v_mfma_f32_16x16x32_bf16 v[80:83], v[142:145], v[206:209], v[80:83]
	v_mfma_f32_16x16x32_bf16 v[72:75], v[158:161], v[206:209], v[72:75]
	v_mfma_f32_16x16x32_bf16 v[124:127], v[154:157], v[186:189], v[124:127]
	v_mfma_f32_16x16x32_bf16 v[120:123], v[162:165], v[186:189], v[120:123]
	v_mfma_f32_16x16x32_bf16 v[116:119], v[154:157], v[194:197], v[116:119]
	v_mfma_f32_16x16x32_bf16 v[112:115], v[162:165], v[194:197], v[112:115]
	v_mfma_f32_16x16x32_bf16 v[96:99], v[154:157], v[202:205], v[96:99]
	v_mfma_f32_16x16x32_bf16 v[88:91], v[162:165], v[202:205], v[88:91]
	v_mfma_f32_16x16x32_bf16 v[80:83], v[154:157], v[210:213], v[80:83]
	v_mfma_f32_16x16x32_bf16 v[72:75], v[162:165], v[210:213], v[72:75]
	s_setprio 0
	s_setprio 1
	v_mfma_f32_16x16x32_bf16 v[108:111], v[166:169], v[182:185], v[108:111]
	v_mfma_f32_16x16x32_bf16 v[104:107], v[174:177], v[182:185], v[104:107]
	v_mfma_f32_16x16x32_bf16 v[100:103], v[166:169], v[190:193], v[100:103]
	v_mfma_f32_16x16x32_bf16 v[92:95], v[174:177], v[190:193], v[92:95]
	v_mfma_f32_16x16x32_bf16 v[84:87], v[166:169], v[198:201], v[84:87]
	v_mfma_f32_16x16x32_bf16 v[76:79], v[174:177], v[198:201], v[76:79]
	v_mfma_f32_16x16x32_bf16 v[68:71], v[166:169], v[206:209], v[68:71]
	v_mfma_f32_16x16x32_bf16 v[64:67], v[174:177], v[206:209], v[64:67]
	v_mfma_f32_16x16x32_bf16 v[108:111], v[170:173], v[186:189], v[108:111]
	v_mfma_f32_16x16x32_bf16 v[104:107], v[178:181], v[186:189], v[104:107]
	v_mfma_f32_16x16x32_bf16 v[100:103], v[170:173], v[194:197], v[100:103]
	v_mfma_f32_16x16x32_bf16 v[92:95], v[178:181], v[194:197], v[92:95]
	v_mfma_f32_16x16x32_bf16 v[84:87], v[170:173], v[202:205], v[84:87]
	v_mfma_f32_16x16x32_bf16 v[76:79], v[178:181], v[202:205], v[76:79]
	v_mfma_f32_16x16x32_bf16 v[68:71], v[170:173], v[210:213], v[68:71]
	v_mfma_f32_16x16x32_bf16 v[64:67], v[178:181], v[210:213], v[64:67]
	s_setprio 0
	s_barrier
; #define PG8_STAGE(bufoff, gbase, voff) do { _Pragma("unroll") for (int _i = 0; _i < 2; ++_i) \
;         __builtin_amdgcn_global_load_lds((const unsigned*)((const char*)(gbase) + (voff)[_i]), (PG8_LAS unsigned*)(lds + (bufoff) + ldsw + _i * 8192), 16, 0, 0); } while (0)
; #define PG8_LDA(dst, b, h) do { _Pragma("unroll") for (int m = 0; m < 4; ++m) _Pragma("unroll") for (int k = 0; k < 2; ++k) dst[m][k] = *(const PG8_LAS bf16x8*)(lds + PG8_SA(b, h) + aoff + m * 2048 + k * 1024); } while (0)
; #define PG8_LDB(dst, b, h) do { _Pragma("unroll") for (int n = 0; n < 2; ++n) _Pragma("unroll") for (int k = 0; k < 2; ++k) dst[n][k] = *(const PG8_LAS bf16x8*)(lds + PG8_SB(b, h) + boff + n * 2048 + k * 1024); } while (0)
; #define PG8_MMA(ai, bj, At, Bt) do { __builtin_amdgcn_s_setprio(1); _Pragma("unroll") for (int m = 0; m < 4; ++m) _Pragma("unroll") for (int n = 0; n < 2; ++n) _Pragma("unroll") for (int k = 0; k < 2; ++k) \
;         acc[ai][bj][m][n] = __builtin_amdgcn_mfma_f32_16x16x32_bf16(Bt[n][k], At[m][k], acc[ai][bj][m][n], 0, 0, 0); __builtin_amdgcn_s_setprio(0); } while (0)
; #define PG8_WAIT_V(n) asm volatile("s_waitcnt vmcnt(" #n ")" ::: "memory")
; #define PG8_WAIT_L(n) asm volatile("s_waitcnt lgkmcnt(" #n ")" ::: "memory")
; #define PG8_BAR __builtin_amdgcn_s_barrier()
; #define PG8_SCHED __builtin_amdgcn_sched_barrier(0)
; template <class Epi, class Sched, bool ALIGN_EPI = false, bool SP2 = false, bool ABLK = false>
; __device__ __forceinline__ void gemm_phase(PG8_LAS unsigned char* lds, const Gemm g, const Sched& S, const Epi& E) {
;     ...
;             PG8_LDB(B0, 1, 0); PG8_LDB(B1, 1, 1); PG8_SCHED; PG8_LDA(At, 1, 0); PG8_STAGE(PG8_SA(0, 1), a2 + hstepA, voffA);
;             PG8_WAIT_V(8); PG8_WAIT_L(0); PG8_BAR; PG8_MMA(0, 0, At, B0); PG8_MMA(0, 1, At, B1); PG8_BAR; PG8_SCHED;
;             PG8_LDA(At, 1, 1); PG8_STAGE(PG8_SB(1, 0), b3, voffB); PG8_STAGE(PG8_SB(1, 1), b3 + hstep, voffB); PG8_STAGE(PG8_SA(1, 0), a3, voffA);
;             PG8_WAIT_V(8); PG8_WAIT_L(0); PG8_BAR; PG8_MMA(1, 0, At, B0); PG8_MMA(1, 1, At, B1); PG8_BAR; PG8_SCHED;
	s_add_i32 s40, s65, s44
	v_lshl_add_u64 v[146:147], v[146:147], 0, s[4:5]
	s_mov_b32 m0, s40
	ds_read_b128 v[182:185], v153 offset:49152
	ds_read_b128 v[186:189], v153 offset:50176
	ds_read_b128 v[190:193], v153 offset:51200
	ds_read_b128 v[194:197], v153 offset:52224
	ds_read_b128 v[198:201], v153 offset:53248
	ds_read_b128 v[202:205], v153 offset:54272
	ds_read_b128 v[206:209], v153 offset:55296
	ds_read_b128 v[210:213], v153 offset:56320
	global_load_lds_dwordx4 v[146:147], off
	s_add_i32 m0, s40, 0x2000
	s_add_u32 s38, s38, 0x100080
	v_lshl_add_u64 v[146:147], v[214:215], 0, s[4:5]
	s_addc_u32 s39, s39, 0
	s_add_i32 s40, s68, s44
	global_load_lds_dwordx4 v[146:147], off
	v_lshl_add_u64 v[146:147], s[38:39], 0, v[132:133]
	s_mov_b32 m0, s40
	s_nop 0
	global_load_lds_dwordx4 v[146:147], off
	v_lshl_add_u64 v[146:147], s[38:39], 0, v[128:129]
	s_add_i32 m0, s40, 0x2000
	s_nop 0
	global_load_lds_dwordx4 v[146:147], off
	v_lshl_add_u64 v[146:147], s[36:37], 0, v[134:135]
	s_mov_b32 m0, s54
	s_nop 0
	global_load_lds_dwordx4 v[146:147], off
	v_lshl_add_u64 v[146:147], s[36:37], 0, v[130:131]
	s_mov_b32 m0, s55
	s_nop 0
	global_load_lds_dwordx4 v[146:147], off
	s_waitcnt vmcnt(8)
	s_waitcnt lgkmcnt(0)
	s_barrier
	s_setprio 1
	s_waitcnt lgkmcnt(0)
	v_mfma_f32_16x16x32_bf16 v[60:63], v[142:145], v[182:185], v[60:63]
	v_mfma_f32_16x16x32_bf16 v[56:59], v[158:161], v[182:185], v[56:59]
	v_mfma_f32_16x16x32_bf16 v[48:51], v[142:145], v[190:193], v[48:51]
	v_mfma_f32_16x16x32_bf16 v[40:43], v[158:161], v[190:193], v[40:43]
	v_mfma_f32_16x16x32_bf16 v[32:35], v[142:145], v[198:201], v[32:35]
	v_mfma_f32_16x16x32_bf16 v[24:27], v[158:161], v[198:201], v[24:27]
	v_mfma_f32_16x16x32_bf16 v[16:19], v[142:145], v[206:209], v[16:19]
	v_mfma_f32_16x16x32_bf16 v[8:11], v[158:161], v[206:209], v[8:11]
	v_mfma_f32_16x16x32_bf16 v[60:63], v[154:157], v[186:189], v[60:63]
	v_mfma_f32_16x16x32_bf16 v[56:59], v[162:165], v[186:189], v[56:59]
	v_mfma_f32_16x16x32_bf16 v[48:51], v[154:157], v[194:197], v[48:51]
	v_mfma_f32_16x16x32_bf16 v[40:43], v[162:165], v[194:197], v[40:43]
	v_mfma_f32_16x16x32_bf16 v[32:35], v[154:157], v[202:205], v[32:35]
	v_mfma_f32_16x16x32_bf16 v[24:27], v[162:165], v[202:205], v[24:27]
	v_mfma_f32_16x16x32_bf16 v[16:19], v[154:157], v[210:213], v[16:19]
	v_mfma_f32_16x16x32_bf16 v[8:11], v[162:165], v[210:213], v[8:11]
	s_setprio 0
	s_setprio 1
	v_mfma_f32_16x16x32_bf16 v[52:55], v[166:169], v[182:185], v[52:55]
	v_mfma_f32_16x16x32_bf16 v[44:47], v[174:177], v[182:185], v[44:47]
	v_mfma_f32_16x16x32_bf16 v[36:39], v[166:169], v[190:193], v[36:39]
	v_mfma_f32_16x16x32_bf16 v[28:31], v[174:177], v[190:193], v[28:31]
	v_mfma_f32_16x16x32_bf16 v[20:23], v[166:169], v[198:201], v[20:23]
	v_mfma_f32_16x16x32_bf16 v[12:15], v[174:177], v[198:201], v[12:15]
	v_mfma_f32_16x16x32_bf16 v[4:7], v[166:169], v[206:209], v[4:7]
	v_mfma_f32_16x16x32_bf16 v[0:3], v[174:177], v[206:209], v[0:3]
	v_mfma_f32_16x16x32_bf16 v[52:55], v[170:173], v[186:189], v[52:55]
	v_mfma_f32_16x16x32_bf16 v[44:47], v[178:181], v[186:189], v[44:47]
	v_mfma_f32_16x16x32_bf16 v[36:39], v[170:173], v[194:197], v[36:39]
	v_mfma_f32_16x16x32_bf16 v[28:31], v[178:181], v[194:197], v[28:31]
	v_mfma_f32_16x16x32_bf16 v[20:23], v[170:173], v[202:205], v[20:23]
	v_mfma_f32_16x16x32_bf16 v[12:15], v[178:181], v[202:205], v[12:15]
	v_mfma_f32_16x16x32_bf16 v[4:7], v[170:173], v[210:213], v[4:7]
	v_mfma_f32_16x16x32_bf16 v[0:3], v[178:181], v[210:213], v[0:3]
	s_setprio 0
	s_barrier
	s_add_i32 s64, s64, 2
	s_add_u32 s62, s62, 0x100
	s_addc_u32 s63, s63, 0
	s_add_u32 s34, s34, 0x10000
	s_addc_u32 s35, s35, 0
	s_cmp_gt_u32 s64, 61
	s_cbranch_scc0 .LBB0_578
	s_branch .Lp5_kdone
	.p2align 6
